# gemm_z last row group tiles moved to even slots 0..22 (no WG gets three rope tiles)
# baseline (speedup 1.0000x reference)
; __device__ void phase_gemm_z(const P& p, int vb, int nvb, char* smem) {
;     ...
;   const int xcd = vb & 7, slot = vb >> 3, nslot = nvb >> 3;
;   for (int li = xs ? slot : vb; li < (xs ? 33 * 12 : 264 * 12); li += (xs ? nslot : nvb)) {
;     const int mt = xs ? (li / 12) * 8 + xcd : li / 12, nt = li % 12;
;     const char* arow[4]; const bool az[4] = {false, false, false, false};
; #pragma unroll
;     for (int i = 0; i < 4; i++) arow[i] = p.ws + WS_HB + (size_t)(mt * 128 + r0 + 32 * i) * 2048;
;     gemm_core<0, false, false, 1024>(smem, arow, az, (const uint16_t*)(p.ws + WS_WT_IN), nt * 128, (nt * 4) / 3);
.LBB0_61:
	s_or_b64 exec, exec, s[12:13]
	s_cmpk_ge_i32 s38, 0x180
	s_cbranch_scc1 .LBB0_80
	s_add_i32 s38, s38, s57
	s_cmpk_lt_i32 s38, 0x180
	s_cbranch_scc1 .LBB0_62
	s_bitcmp1_b32 s56, 0
	s_cbranch_scc1 .LBB0_80
	s_cmpk_ge_u32 s56, 24
	s_cbranch_scc1 .LBB0_80
	s_lshr_b32 s38, s56, 1
	s_addk_i32 s38, 0x180

; __device__ void phase_gather(const P& p, int vb, int nvb, char* smem) {
;     ...
; #pragma unroll 1
;     for (int b0 = 0; b0 < 128; b0 += 8) {
;       float dp[8];
; #pragma unroll
;       for (int u = 0; u < 8; u++) {
;         const uint32_t key = mykl[b0 + u];
;         const int e = (int)(key >> 7);
;         const uint4* up = (const uint4*)(U + (size_t)e * 1024 + 16 * j);
;         uint4 uu[4];
; #pragma unroll
;         for (int i = 0; i < 4; i++) uu[i] = up[i * 16];
;         f32x2 d2 = f32x2{0.f, 0.f};
; #pragma unroll
;         for (int i = 0; i < 4; i++) {
;           const uint32_t w[4] = {uu[i].x, uu[i].y, uu[i].z, uu[i].w};
; #pragma unroll
;           for (int q = 0; q < 4; q++) {
;             d2 += __builtin_amdgcn_cvt_pk_f32_fp8((int)w[q], false) * xf[i * 8 + q * 2 + 0];
;             d2 += __builtin_amdgcn_cvt_pk_f32_fp8((int)w[q], true) * xf[i * 8 + q * 2 + 1];
;           }
;         }
;         dp[u] = d2.x + d2.y;
.Lgu_iter:
	s_and_b32 s27, s26, 7
	s_cmp_lg_u32 s27, 0
	s_cbranch_scc1 .Lgu_body
	s_lshr_b32 s27, s26, 3
	s_and_b32 s27, s27, 3
	s_cmp_eq_u32 s27, 0
	s_cbranch_scc1 .Lgu_s_0
	s_cmp_eq_u32 s27, 1
	s_cbranch_scc1 .Lgu_s_1
	s_cmp_eq_u32 s27, 2
	s_cbranch_scc1 .Lgu_s_2
	v_mov_b32_e32 v214, v80
	v_mov_b32_e32 v215, v81
	v_mov_b32_e32 v216, v82
	v_mov_b32_e32 v217, v83
	v_mov_b32_e32 v218, v84
	v_mov_b32_e32 v219, v85
	v_mov_b32_e32 v220, v86
	v_mov_b32_e32 v221, v87
	v_mov_b32_e32 v222, v88
	v_mov_b32_e32 v223, v89
	v_mov_b32_e32 v224, v90
	v_mov_b32_e32 v225, v91
	v_mov_b32_e32 v226, v92
	v_mov_b32_e32 v227, v93
	v_mov_b32_e32 v228, v94
	v_mov_b32_e32 v229, v95
	s_branch .Lgu_s_x

; __device__ void phase_gather(const P& p, int vb, int nvb, char* smem) {
;     ...
; #pragma unroll 1
;     for (int b0 = 0; b0 < 128; b0 += 8) {
;       float dp[8];
; #pragma unroll
;       for (int u = 0; u < 8; u++) {
;         const uint32_t key = mykl[b0 + u];
;         const int e = (int)(key >> 7);
;         const uint4* up = (const uint4*)(U + (size_t)e * 1024 + 16 * j);
;         uint4 uu[4];
; #pragma unroll
;         for (int i = 0; i < 4; i++) uu[i] = up[i * 16];
;         f32x2 d2 = f32x2{0.f, 0.f};
; #pragma unroll
;         for (int i = 0; i < 4; i++) {
;           const uint32_t w[4] = {uu[i].x, uu[i].y, uu[i].z, uu[i].w};
; #pragma unroll
;           for (int q = 0; q < 4; q++) {
;             d2 += __builtin_amdgcn_cvt_pk_f32_fp8((int)w[q], false) * xf[i * 8 + q * 2 + 0];
;             d2 += __builtin_amdgcn_cvt_pk_f32_fp8((int)w[q], true) * xf[i * 8 + q * 2 + 1];
;           }
;         }
;         dp[u] = d2.x + d2.y;
;       }
.Lgu_s_x:
.Lgu_body:
	s_cmp_eq_u32 s26, 31
	s_cbranch_scc1 .Lgu_last
	s_waitcnt lgkmcnt(0)
	s_waitcnt vmcnt(15)
	v_cvt_pk_f32_fp8_e32 v[104:105], v150
	v_cvt_pk_f32_fp8_sdwa v[106:107], v150 src0_sel:WORD_1
	v_pk_mul_f32 v[112:113], v[104:105], v[214:215]
	v_cvt_pk_f32_fp8_e32 v[108:109], v151
	v_pk_fma_f32 v[112:113], v[106:107], v[216:217], v[112:113]
	v_cvt_pk_f32_fp8_sdwa v[110:111], v151 src0_sel:WORD_1
	v_pk_fma_f32 v[112:113], v[108:109], v[218:219], v[112:113]
	v_cvt_pk_f32_fp8_e32 v[104:105], v152
	v_pk_fma_f32 v[112:113], v[110:111], v[220:221], v[112:113]
	v_cvt_pk_f32_fp8_sdwa v[106:107], v152 src0_sel:WORD_1
	v_pk_fma_f32 v[112:113], v[104:105], v[222:223], v[112:113]
	v_cvt_pk_f32_fp8_e32 v[108:109], v153
	v_pk_fma_f32 v[112:113], v[106:107], v[224:225], v[112:113]
	v_cvt_pk_f32_fp8_sdwa v[110:111], v153 src0_sel:WORD_1
	v_pk_fma_f32 v[112:113], v[108:109], v[226:227], v[112:113]
	v_and_or_b32 v8, v0, s66, v230
	v_pk_fma_f32 v[112:113], v[110:111], v[228:229], v[112:113]
	global_load_dwordx4 v[150:153], v8, s[98:99]
	v_add_f32_e32 v116, v112, v113
	s_waitcnt vmcnt(15)
	v_cvt_pk_f32_fp8_e32 v[104:105], v154
	v_cvt_pk_f32_fp8_sdwa v[106:107], v154 src0_sel:WORD_1
	v_pk_mul_f32 v[112:113], v[104:105], v[214:215]
	v_cvt_pk_f32_fp8_e32 v[108:109], v155
	v_pk_fma_f32 v[112:113], v[106:107], v[216:217], v[112:113]
	v_cvt_pk_f32_fp8_sdwa v[110:111], v155 src0_sel:WORD_1
	v_pk_fma_f32 v[112:113], v[108:109], v[218:219], v[112:113]
	v_cvt_pk_f32_fp8_e32 v[104:105], v156
	v_pk_fma_f32 v[112:113], v[110:111], v[220:221], v[112:113]
	v_cvt_pk_f32_fp8_sdwa v[106:107], v156 src0_sel:WORD_1
	v_pk_fma_f32 v[112:113], v[104:105], v[222:223], v[112:113]
	v_cvt_pk_f32_fp8_e32 v[108:109], v157
	v_pk_fma_f32 v[112:113], v[106:107], v[224:225], v[112:113]
	v_cvt_pk_f32_fp8_sdwa v[110:111], v157 src0_sel:WORD_1
	v_pk_fma_f32 v[112:113], v[108:109], v[226:227], v[112:113]
	v_and_or_b32 v9, v1, s66, v230
	v_pk_fma_f32 v[112:113], v[110:111], v[228:229], v[112:113]
	global_load_dwordx4 v[154:157], v9, s[98:99]
	v_add_f32_e32 v117, v112, v113
	ds_read_b128 v[4:7], v254 offset:16
	s_waitcnt vmcnt(15)
	v_cvt_pk_f32_fp8_e32 v[104:105], v158
	v_cvt_pk_f32_fp8_sdwa v[106:107], v158 src0_sel:WORD_1
	v_pk_mul_f32 v[112:113], v[104:105], v[214:215]
	v_cvt_pk_f32_fp8_e32 v[108:109], v159
	v_pk_fma_f32 v[112:113], v[106:107], v[216:217], v[112:113]
	v_cvt_pk_f32_fp8_sdwa v[110:111], v159 src0_sel:WORD_1
	v_pk_fma_f32 v[112:113], v[108:109], v[218:219], v[112:113]
	v_cvt_pk_f32_fp8_e32 v[104:105], v160
	v_pk_fma_f32 v[112:113], v[110:111], v[220:221], v[112:113]
	v_cvt_pk_f32_fp8_sdwa v[106:107], v160 src0_sel:WORD_1
	v_pk_fma_f32 v[112:113], v[104:105], v[222:223], v[112:113]
	v_cvt_pk_f32_fp8_e32 v[108:109], v161
	v_pk_fma_f32 v[112:113], v[106:107], v[224:225], v[112:113]
	v_cvt_pk_f32_fp8_sdwa v[110:111], v161 src0_sel:WORD_1
	v_pk_fma_f32 v[112:113], v[108:109], v[226:227], v[112:113]
	v_and_or_b32 v8, v2, s66, v230
	v_pk_fma_f32 v[112:113], v[110:111], v[228:229], v[112:113]
	global_load_dwordx4 v[158:161], v8, s[98:99]
	v_add_f32_e32 v118, v112, v113
	s_waitcnt vmcnt(15)
	v_cvt_pk_f32_fp8_e32 v[104:105], v162
	v_cvt_pk_f32_fp8_sdwa v[106:107], v162 src0_sel:WORD_1
	v_pk_mul_f32 v[112:113], v[104:105], v[214:215]
	v_cvt_pk_f32_fp8_e32 v[108:109], v163
	v_pk_fma_f32 v[112:113], v[106:107], v[216:217], v[112:113]
	v_cvt_pk_f32_fp8_sdwa v[110:111], v163 src0_sel:WORD_1
	v_pk_fma_f32 v[112:113], v[108:109], v[218:219], v[112:113]
	v_cvt_pk_f32_fp8_e32 v[104:105], v164
	v_pk_fma_f32 v[112:113], v[110:111], v[220:221], v[112:113]
	v_cvt_pk_f32_fp8_sdwa v[106:107], v164 src0_sel:WORD_1
	v_pk_fma_f32 v[112:113], v[104:105], v[222:223], v[112:113]
	v_cvt_pk_f32_fp8_e32 v[108:109], v165
	v_pk_fma_f32 v[112:113], v[106:107], v[224:225], v[112:113]
	v_cvt_pk_f32_fp8_sdwa v[110:111], v165 src0_sel:WORD_1
	v_pk_fma_f32 v[112:113], v[108:109], v[226:227], v[112:113]
	v_and_or_b32 v9, v3, s66, v230
	v_pk_fma_f32 v[112:113], v[110:111], v[228:229], v[112:113]
	global_load_dwordx4 v[162:165], v9, s[98:99]
	v_add_f32_e32 v119, v112, v113
	s_waitcnt lgkmcnt(0)
	s_waitcnt vmcnt(15)
	v_cvt_pk_f32_fp8_e32 v[104:105], v166
	v_cvt_pk_f32_fp8_sdwa v[106:107], v166 src0_sel:WORD_1
	v_pk_mul_f32 v[112:113], v[104:105], v[214:215]
	v_cvt_pk_f32_fp8_e32 v[108:109], v167
	v_pk_fma_f32 v[112:113], v[106:107], v[216:217], v[112:113]
	v_cvt_pk_f32_fp8_sdwa v[110:111], v167 src0_sel:WORD_1
	v_pk_fma_f32 v[112:113], v[108:109], v[218:219], v[112:113]
	v_cvt_pk_f32_fp8_e32 v[104:105], v168
	v_pk_fma_f32 v[112:113], v[110:111], v[220:221], v[112:113]
	v_cvt_pk_f32_fp8_sdwa v[106:107], v168 src0_sel:WORD_1
	v_pk_fma_f32 v[112:113], v[104:105], v[222:223], v[112:113]
	v_cvt_pk_f32_fp8_e32 v[108:109], v169
	v_pk_fma_f32 v[112:113], v[106:107], v[224:225], v[112:113]
	v_cvt_pk_f32_fp8_sdwa v[110:111], v169 src0_sel:WORD_1
	v_pk_fma_f32 v[112:113], v[108:109], v[226:227], v[112:113]
	v_and_or_b32 v8, v4, s66, v230
	v_pk_fma_f32 v[112:113], v[110:111], v[228:229], v[112:113]
	global_load_dwordx4 v[166:169], v8, s[98:99]
	v_add_f32_e32 v120, v112, v113
	s_waitcnt vmcnt(15)
	v_cvt_pk_f32_fp8_e32 v[104:105], v170
	v_cvt_pk_f32_fp8_sdwa v[106:107], v170 src0_sel:WORD_1
	v_pk_mul_f32 v[112:113], v[104:105], v[214:215]
	v_cvt_pk_f32_fp8_e32 v[108:109], v171
	v_pk_fma_f32 v[112:113], v[106:107], v[216:217], v[112:113]
	v_cvt_pk_f32_fp8_sdwa v[110:111], v171 src0_sel:WORD_1
	v_pk_fma_f32 v[112:113], v[108:109], v[218:219], v[112:113]
	v_cvt_pk_f32_fp8_e32 v[104:105], v172
	v_pk_fma_f32 v[112:113], v[110:111], v[220:221], v[112:113]
	v_cvt_pk_f32_fp8_sdwa v[106:107], v172 src0_sel:WORD_1
	v_pk_fma_f32 v[112:113], v[104:105], v[222:223], v[112:113]
	v_cvt_pk_f32_fp8_e32 v[108:109], v173
	v_pk_fma_f32 v[112:113], v[106:107], v[224:225], v[112:113]
	v_cvt_pk_f32_fp8_sdwa v[110:111], v173 src0_sel:WORD_1
	v_pk_fma_f32 v[112:113], v[108:109], v[226:227], v[112:113]
	v_and_or_b32 v9, v5, s66, v230
	v_pk_fma_f32 v[112:113], v[110:111], v[228:229], v[112:113]
	global_load_dwordx4 v[170:173], v9, s[98:99]
	v_add_f32_e32 v121, v112, v113
	ds_read_b128 v[0:3], v254 offset:32
	s_waitcnt vmcnt(15)
; __device__ void phase_gather(const P& p, int vb, int nvb, char* smem) {
;     ...
; #pragma unroll 1
;     for (int b0 = 0; b0 < 128; b0 += 8) {
;       float dp[8];
; #pragma unroll
;       for (int u = 0; u < 8; u++) {
;         const uint32_t key = mykl[b0 + u];
;         const int e = (int)(key >> 7);
;         const uint4* up = (const uint4*)(U + (size_t)e * 1024 + 16 * j);
;         uint4 uu[4];
; #pragma unroll
;         for (int i = 0; i < 4; i++) uu[i] = up[i * 16];
;         f32x2 d2 = f32x2{0.f, 0.f};
; #pragma unroll
;         for (int i = 0; i < 4; i++) {
;           const uint32_t w[4] = {uu[i].x, uu[i].y, uu[i].z, uu[i].w};
; #pragma unroll
;           for (int q = 0; q < 4; q++) {
;             d2 += __builtin_amdgcn_cvt_pk_f32_fp8((int)w[q], false) * xf[i * 8 + q * 2 + 0];
;             d2 += __builtin_amdgcn_cvt_pk_f32_fp8((int)w[q], true) * xf[i * 8 + q * 2 + 1];
;           }
;         }
;         dp[u] = d2.x + d2.y;
;       }
;       const bool h8 = (j & 8) != 0, h4 = (j & 4) != 0, h2b = (j & 2) != 0;
;       float q4[4], q2[2];
; #pragma unroll
;       for (int k = 0; k < 4; k++) { const float snd = h8 ? dp[k] : dp[k + 4], kp = h8 ? dp[k + 4] : dp[k]; q4[k] = kp + __shfl_xor(snd, 8); }
; #pragma unroll
;       for (int k = 0; k < 2; k++) { const float snd = h4 ? q4[k] : q4[k + 2], kp = h4 ? q4[k + 2] : q4[k]; q2[k] = kp + __shfl_xor(snd, 4); }
;       const float snd1 = h2b ? q2[0] : q2[1], kp1 = h2b ? q2[1] : q2[0];
;       float q1 = kp1 + __shfl_xor(snd1, 2);
;       q1 += __shfl_xor(q1, 1);
;       if ((j & 1) == 0) mywl[b0 + (j >> 1)] = q1;
	v_cvt_pk_f32_fp8_e32 v[104:105], v174
	v_cvt_pk_f32_fp8_sdwa v[106:107], v174 src0_sel:WORD_1
	v_pk_mul_f32 v[112:113], v[104:105], v[214:215]
	v_cvt_pk_f32_fp8_e32 v[108:109], v175
	v_pk_fma_f32 v[112:113], v[106:107], v[216:217], v[112:113]
	v_cvt_pk_f32_fp8_sdwa v[110:111], v175 src0_sel:WORD_1
	v_pk_fma_f32 v[112:113], v[108:109], v[218:219], v[112:113]
	v_cvt_pk_f32_fp8_e32 v[104:105], v176
	v_pk_fma_f32 v[112:113], v[110:111], v[220:221], v[112:113]
	v_cvt_pk_f32_fp8_sdwa v[106:107], v176 src0_sel:WORD_1
	v_pk_fma_f32 v[112:113], v[104:105], v[222:223], v[112:113]
	v_cvt_pk_f32_fp8_e32 v[108:109], v177
	v_pk_fma_f32 v[112:113], v[106:107], v[224:225], v[112:113]
	v_cvt_pk_f32_fp8_sdwa v[110:111], v177 src0_sel:WORD_1
	v_pk_fma_f32 v[112:113], v[108:109], v[226:227], v[112:113]
	v_and_or_b32 v8, v6, s66, v230
	v_pk_fma_f32 v[112:113], v[110:111], v[228:229], v[112:113]
	global_load_dwordx4 v[174:177], v8, s[98:99]
	v_add_f32_e32 v122, v112, v113
	s_waitcnt vmcnt(15)
	v_cvt_pk_f32_fp8_e32 v[104:105], v178
	v_cvt_pk_f32_fp8_sdwa v[106:107], v178 src0_sel:WORD_1
	v_pk_mul_f32 v[112:113], v[104:105], v[214:215]
	v_cvt_pk_f32_fp8_e32 v[108:109], v179
	v_pk_fma_f32 v[112:113], v[106:107], v[216:217], v[112:113]
	v_cvt_pk_f32_fp8_sdwa v[110:111], v179 src0_sel:WORD_1
	v_pk_fma_f32 v[112:113], v[108:109], v[218:219], v[112:113]
	v_cvt_pk_f32_fp8_e32 v[104:105], v180
	v_pk_fma_f32 v[112:113], v[110:111], v[220:221], v[112:113]
	v_cvt_pk_f32_fp8_sdwa v[106:107], v180 src0_sel:WORD_1
	v_pk_fma_f32 v[112:113], v[104:105], v[222:223], v[112:113]
	v_cvt_pk_f32_fp8_e32 v[108:109], v181
	v_pk_fma_f32 v[112:113], v[106:107], v[224:225], v[112:113]
	v_cvt_pk_f32_fp8_sdwa v[110:111], v181 src0_sel:WORD_1
	v_pk_fma_f32 v[112:113], v[108:109], v[226:227], v[112:113]
	v_and_or_b32 v9, v7, s66, v230
	v_pk_fma_f32 v[112:113], v[110:111], v[228:229], v[112:113]
	global_load_dwordx4 v[178:181], v9, s[98:99]
	v_add_f32_e32 v123, v112, v113
	v_add_f32_dpp v10, v116, v116 row_ror:8 row_mask:0xf bank_mask:0x3
	v_add_f32_dpp v11, v117, v117 row_ror:8 row_mask:0xf bank_mask:0x3
	v_add_f32_dpp v12, v118, v118 row_ror:8 row_mask:0xf bank_mask:0x3
	v_add_f32_dpp v124, v119, v119 row_ror:8 row_mask:0xf bank_mask:0x3
	v_add_f32_dpp v10, v120, v120 row_ror:8 row_mask:0xf bank_mask:0xc
	v_add_f32_dpp v11, v121, v121 row_ror:8 row_mask:0xf bank_mask:0xc
	v_add_f32_dpp v12, v122, v122 row_ror:8 row_mask:0xf bank_mask:0xc
	v_add_f32_dpp v124, v123, v123 row_ror:8 row_mask:0xf bank_mask:0xc
	s_nop 0
	v_add_f32_dpp v125, v10, v10 row_shl:4 row_mask:0xf bank_mask:0x5
	v_add_f32_dpp v246, v11, v11 row_shl:4 row_mask:0xf bank_mask:0x5
	v_add_f32_dpp v125, v12, v12 row_shr:4 row_mask:0xf bank_mask:0xa
	v_add_f32_dpp v246, v124, v124 row_shr:4 row_mask:0xf bank_mask:0xa
	s_nop 1
	v_add_f32_dpp v247, v125, v125 quad_perm:[2,3,0,1] row_mask:0xf bank_mask:0xf
	v_add_f32_dpp v249, v246, v246 quad_perm:[2,3,0,1] row_mask:0xf bank_mask:0xf
	s_nop 0
	v_cndmask_b32_e64 v252, v249, v247, s[2:3]
	s_nop 1
	v_add_f32_dpp v253, v252, v252 quad_perm:[1,0,3,2] row_mask:0xf bank_mask:0xf
	s_and_saveexec_b64 s[20:21], s[4:5]
	ds_add_f32 v251, v253 offset:2048
	s_mov_b64 exec, s[20:21]
	s_waitcnt lgkmcnt(0)
	s_waitcnt vmcnt(15)
	v_cvt_pk_f32_fp8_e32 v[104:105], v182
	v_cvt_pk_f32_fp8_sdwa v[106:107], v182 src0_sel:WORD_1
	v_pk_mul_f32 v[112:113], v[104:105], v[214:215]
	v_cvt_pk_f32_fp8_e32 v[108:109], v183
	v_pk_fma_f32 v[112:113], v[106:107], v[216:217], v[112:113]
	v_cvt_pk_f32_fp8_sdwa v[110:111], v183 src0_sel:WORD_1
	v_pk_fma_f32 v[112:113], v[108:109], v[218:219], v[112:113]
	v_cvt_pk_f32_fp8_e32 v[104:105], v184
	v_pk_fma_f32 v[112:113], v[110:111], v[220:221], v[112:113]
	v_cvt_pk_f32_fp8_sdwa v[106:107], v184 src0_sel:WORD_1
	v_pk_fma_f32 v[112:113], v[104:105], v[222:223], v[112:113]
	v_cvt_pk_f32_fp8_e32 v[108:109], v185
	v_pk_fma_f32 v[112:113], v[106:107], v[224:225], v[112:113]
	v_cvt_pk_f32_fp8_sdwa v[110:111], v185 src0_sel:WORD_1
	v_pk_fma_f32 v[112:113], v[108:109], v[226:227], v[112:113]
	v_and_or_b32 v8, v0, s66, v230
	v_pk_fma_f32 v[112:113], v[110:111], v[228:229], v[112:113]
	global_load_dwordx4 v[182:185], v8, s[98:99]
	v_add_f32_e32 v116, v112, v113
	s_waitcnt vmcnt(15)
	v_cvt_pk_f32_fp8_e32 v[104:105], v186
	v_cvt_pk_f32_fp8_sdwa v[106:107], v186 src0_sel:WORD_1
	v_pk_mul_f32 v[112:113], v[104:105], v[214:215]
	v_cvt_pk_f32_fp8_e32 v[108:109], v187
	v_pk_fma_f32 v[112:113], v[106:107], v[216:217], v[112:113]
	v_cvt_pk_f32_fp8_sdwa v[110:111], v187 src0_sel:WORD_1
	v_pk_fma_f32 v[112:113], v[108:109], v[218:219], v[112:113]
	v_cvt_pk_f32_fp8_e32 v[104:105], v188
	v_pk_fma_f32 v[112:113], v[110:111], v[220:221], v[112:113]
	v_cvt_pk_f32_fp8_sdwa v[106:107], v188 src0_sel:WORD_1
	v_pk_fma_f32 v[112:113], v[104:105], v[222:223], v[112:113]
	v_cvt_pk_f32_fp8_e32 v[108:109], v189
	v_pk_fma_f32 v[112:113], v[106:107], v[224:225], v[112:113]
	v_cvt_pk_f32_fp8_sdwa v[110:111], v189 src0_sel:WORD_1
	v_pk_fma_f32 v[112:113], v[108:109], v[226:227], v[112:113]
	v_and_or_b32 v9, v1, s66, v230
	v_pk_fma_f32 v[112:113], v[110:111], v[228:229], v[112:113]
	global_load_dwordx4 v[186:189], v9, s[98:99]
	v_add_f32_e32 v117, v112, v113
	ds_read_b128 v[4:7], v254 offset:48
	s_waitcnt vmcnt(15)
; __device__ void phase_gather(const P& p, int vb, int nvb, char* smem) {
;     ...
;     for (int b0 = 0; b0 < 128; b0 += 8) {
;       float dp[8];
; #pragma unroll
;       for (int u = 0; u < 8; u++) {
;         const uint32_t key = mykl[b0 + u];
;         const int e = (int)(key >> 7);
;         const uint4* up = (const uint4*)(U + (size_t)e * 1024 + 16 * j);
;         uint4 uu[4];
; #pragma unroll
;         for (int i = 0; i < 4; i++) uu[i] = up[i * 16];
;         f32x2 d2 = f32x2{0.f, 0.f};
; #pragma unroll
;         for (int i = 0; i < 4; i++) {
;           const uint32_t w[4] = {uu[i].x, uu[i].y, uu[i].z, uu[i].w};
; #pragma unroll
;           for (int q = 0; q < 4; q++) {
;             d2 += __builtin_amdgcn_cvt_pk_f32_fp8((int)w[q], false) * xf[i * 8 + q * 2 + 0];
;             d2 += __builtin_amdgcn_cvt_pk_f32_fp8((int)w[q], true) * xf[i * 8 + q * 2 + 1];
;           }
;         }
;         dp[u] = d2.x + d2.y;
;       }
	v_cvt_pk_f32_fp8_e32 v[104:105], v190
	v_cvt_pk_f32_fp8_sdwa v[106:107], v190 src0_sel:WORD_1
	v_pk_mul_f32 v[112:113], v[104:105], v[214:215]
	v_cvt_pk_f32_fp8_e32 v[108:109], v191
	v_pk_fma_f32 v[112:113], v[106:107], v[216:217], v[112:113]
	v_cvt_pk_f32_fp8_sdwa v[110:111], v191 src0_sel:WORD_1
	v_pk_fma_f32 v[112:113], v[108:109], v[218:219], v[112:113]
	v_cvt_pk_f32_fp8_e32 v[104:105], v192
	v_pk_fma_f32 v[112:113], v[110:111], v[220:221], v[112:113]
	v_cvt_pk_f32_fp8_sdwa v[106:107], v192 src0_sel:WORD_1
	v_pk_fma_f32 v[112:113], v[104:105], v[222:223], v[112:113]
	v_cvt_pk_f32_fp8_e32 v[108:109], v193
	v_pk_fma_f32 v[112:113], v[106:107], v[224:225], v[112:113]
	v_cvt_pk_f32_fp8_sdwa v[110:111], v193 src0_sel:WORD_1
	v_pk_fma_f32 v[112:113], v[108:109], v[226:227], v[112:113]
	v_and_or_b32 v8, v2, s66, v230
	v_pk_fma_f32 v[112:113], v[110:111], v[228:229], v[112:113]
	global_load_dwordx4 v[190:193], v8, s[98:99]
	v_add_f32_e32 v118, v112, v113
	s_waitcnt vmcnt(15)
	v_cvt_pk_f32_fp8_e32 v[104:105], v194
	v_cvt_pk_f32_fp8_sdwa v[106:107], v194 src0_sel:WORD_1
	v_pk_mul_f32 v[112:113], v[104:105], v[214:215]
	v_cvt_pk_f32_fp8_e32 v[108:109], v195
	v_pk_fma_f32 v[112:113], v[106:107], v[216:217], v[112:113]
	v_cvt_pk_f32_fp8_sdwa v[110:111], v195 src0_sel:WORD_1
	v_pk_fma_f32 v[112:113], v[108:109], v[218:219], v[112:113]
	v_cvt_pk_f32_fp8_e32 v[104:105], v196
	v_pk_fma_f32 v[112:113], v[110:111], v[220:221], v[112:113]
	v_cvt_pk_f32_fp8_sdwa v[106:107], v196 src0_sel:WORD_1
	v_pk_fma_f32 v[112:113], v[104:105], v[222:223], v[112:113]
	v_cvt_pk_f32_fp8_e32 v[108:109], v197
	v_pk_fma_f32 v[112:113], v[106:107], v[224:225], v[112:113]
	v_cvt_pk_f32_fp8_sdwa v[110:111], v197 src0_sel:WORD_1
	v_pk_fma_f32 v[112:113], v[108:109], v[226:227], v[112:113]
	v_and_or_b32 v9, v3, s66, v230
	v_pk_fma_f32 v[112:113], v[110:111], v[228:229], v[112:113]
	global_load_dwordx4 v[194:197], v9, s[98:99]
	v_add_f32_e32 v119, v112, v113
	s_waitcnt lgkmcnt(0)
	s_waitcnt vmcnt(15)
	v_cvt_pk_f32_fp8_e32 v[104:105], v198
	v_cvt_pk_f32_fp8_sdwa v[106:107], v198 src0_sel:WORD_1
	v_pk_mul_f32 v[112:113], v[104:105], v[214:215]
	v_cvt_pk_f32_fp8_e32 v[108:109], v199
	v_pk_fma_f32 v[112:113], v[106:107], v[216:217], v[112:113]
	v_cvt_pk_f32_fp8_sdwa v[110:111], v199 src0_sel:WORD_1
	v_pk_fma_f32 v[112:113], v[108:109], v[218:219], v[112:113]
	v_cvt_pk_f32_fp8_e32 v[104:105], v200
	v_pk_fma_f32 v[112:113], v[110:111], v[220:221], v[112:113]
	v_cvt_pk_f32_fp8_sdwa v[106:107], v200 src0_sel:WORD_1
	v_pk_fma_f32 v[112:113], v[104:105], v[222:223], v[112:113]
	v_cvt_pk_f32_fp8_e32 v[108:109], v201
	v_pk_fma_f32 v[112:113], v[106:107], v[224:225], v[112:113]
	v_cvt_pk_f32_fp8_sdwa v[110:111], v201 src0_sel:WORD_1
	v_pk_fma_f32 v[112:113], v[108:109], v[226:227], v[112:113]
	v_and_or_b32 v8, v4, s66, v230
	v_pk_fma_f32 v[112:113], v[110:111], v[228:229], v[112:113]
	global_load_dwordx4 v[198:201], v8, s[98:99]
	v_add_f32_e32 v120, v112, v113
	s_add_i32 s27, s26, 2
	s_and_b32 s27, s27, 7
	s_lshl_b32 s27, s27, 6
	v_add_u32_e32 v254, s27, v133
	s_waitcnt vmcnt(15)
	v_cvt_pk_f32_fp8_e32 v[104:105], v202
	v_cvt_pk_f32_fp8_sdwa v[106:107], v202 src0_sel:WORD_1
	v_pk_mul_f32 v[112:113], v[104:105], v[214:215]
	v_cvt_pk_f32_fp8_e32 v[108:109], v203
	v_pk_fma_f32 v[112:113], v[106:107], v[216:217], v[112:113]
	v_cvt_pk_f32_fp8_sdwa v[110:111], v203 src0_sel:WORD_1
	v_pk_fma_f32 v[112:113], v[108:109], v[218:219], v[112:113]
	v_cvt_pk_f32_fp8_e32 v[104:105], v204
	v_pk_fma_f32 v[112:113], v[110:111], v[220:221], v[112:113]
	v_cvt_pk_f32_fp8_sdwa v[106:107], v204 src0_sel:WORD_1
	v_pk_fma_f32 v[112:113], v[104:105], v[222:223], v[112:113]
	v_cvt_pk_f32_fp8_e32 v[108:109], v205
	v_pk_fma_f32 v[112:113], v[106:107], v[224:225], v[112:113]
	v_cvt_pk_f32_fp8_sdwa v[110:111], v205 src0_sel:WORD_1
	v_pk_fma_f32 v[112:113], v[108:109], v[226:227], v[112:113]
	v_and_or_b32 v9, v5, s66, v230
	v_pk_fma_f32 v[112:113], v[110:111], v[228:229], v[112:113]
	global_load_dwordx4 v[202:205], v9, s[98:99]
	v_add_f32_e32 v121, v112, v113
	ds_read_b128 v[0:3], v254
	s_waitcnt vmcnt(15)
; __device__ void phase_gather(const P& p, int vb, int nvb, char* smem) {
;     ...
;       const bool h8 = (j & 8) != 0, h4 = (j & 4) != 0, h2b = (j & 2) != 0;
;       float q4[4], q2[2];
; #pragma unroll
;       for (int k = 0; k < 4; k++) { const float snd = h8 ? dp[k] : dp[k + 4], kp = h8 ? dp[k + 4] : dp[k]; q4[k] = kp + __shfl_xor(snd, 8); }
; #pragma unroll
;       for (int k = 0; k < 2; k++) { const float snd = h4 ? q4[k] : q4[k + 2], kp = h4 ? q4[k + 2] : q4[k]; q2[k] = kp + __shfl_xor(snd, 4); }
;       const float snd1 = h2b ? q2[0] : q2[1], kp1 = h2b ? q2[1] : q2[0];
;       float q1 = kp1 + __shfl_xor(snd1, 2);
;       q1 += __shfl_xor(q1, 1);
;       if ((j & 1) == 0) mywl[b0 + (j >> 1)] = q1;
	v_cvt_pk_f32_fp8_e32 v[104:105], v206
	v_cvt_pk_f32_fp8_sdwa v[106:107], v206 src0_sel:WORD_1
	v_pk_mul_f32 v[112:113], v[104:105], v[214:215]
	v_cvt_pk_f32_fp8_e32 v[108:109], v207
	v_pk_fma_f32 v[112:113], v[106:107], v[216:217], v[112:113]
	v_cvt_pk_f32_fp8_sdwa v[110:111], v207 src0_sel:WORD_1
	v_pk_fma_f32 v[112:113], v[108:109], v[218:219], v[112:113]
	v_cvt_pk_f32_fp8_e32 v[104:105], v208
	v_pk_fma_f32 v[112:113], v[110:111], v[220:221], v[112:113]
	v_cvt_pk_f32_fp8_sdwa v[106:107], v208 src0_sel:WORD_1
	v_pk_fma_f32 v[112:113], v[104:105], v[222:223], v[112:113]
	v_cvt_pk_f32_fp8_e32 v[108:109], v209
	v_pk_fma_f32 v[112:113], v[106:107], v[224:225], v[112:113]
	v_cvt_pk_f32_fp8_sdwa v[110:111], v209 src0_sel:WORD_1
	v_pk_fma_f32 v[112:113], v[108:109], v[226:227], v[112:113]
	v_and_or_b32 v8, v6, s66, v230
	v_pk_fma_f32 v[112:113], v[110:111], v[228:229], v[112:113]
	global_load_dwordx4 v[206:209], v8, s[98:99]
	v_add_f32_e32 v122, v112, v113
	s_waitcnt vmcnt(15)
	v_cvt_pk_f32_fp8_e32 v[104:105], v210
	v_cvt_pk_f32_fp8_sdwa v[106:107], v210 src0_sel:WORD_1
	v_pk_mul_f32 v[112:113], v[104:105], v[214:215]
	v_cvt_pk_f32_fp8_e32 v[108:109], v211
	v_pk_fma_f32 v[112:113], v[106:107], v[216:217], v[112:113]
	v_cvt_pk_f32_fp8_sdwa v[110:111], v211 src0_sel:WORD_1
	v_pk_fma_f32 v[112:113], v[108:109], v[218:219], v[112:113]
	v_cvt_pk_f32_fp8_e32 v[104:105], v212
	v_pk_fma_f32 v[112:113], v[110:111], v[220:221], v[112:113]
	v_cvt_pk_f32_fp8_sdwa v[106:107], v212 src0_sel:WORD_1
	v_pk_fma_f32 v[112:113], v[104:105], v[222:223], v[112:113]
	v_cvt_pk_f32_fp8_e32 v[108:109], v213
	v_pk_fma_f32 v[112:113], v[106:107], v[224:225], v[112:113]
	v_cvt_pk_f32_fp8_sdwa v[110:111], v213 src0_sel:WORD_1
	v_pk_fma_f32 v[112:113], v[108:109], v[226:227], v[112:113]
	v_and_or_b32 v9, v7, s66, v230
	v_pk_fma_f32 v[112:113], v[110:111], v[228:229], v[112:113]
	global_load_dwordx4 v[210:213], v9, s[98:99]
	v_add_f32_e32 v123, v112, v113
	v_add_f32_dpp v10, v116, v116 row_ror:8 row_mask:0xf bank_mask:0x3
	v_add_f32_dpp v11, v117, v117 row_ror:8 row_mask:0xf bank_mask:0x3
	v_add_f32_dpp v12, v118, v118 row_ror:8 row_mask:0xf bank_mask:0x3
	v_add_f32_dpp v124, v119, v119 row_ror:8 row_mask:0xf bank_mask:0x3
	v_add_f32_dpp v10, v120, v120 row_ror:8 row_mask:0xf bank_mask:0xc
	v_add_f32_dpp v11, v121, v121 row_ror:8 row_mask:0xf bank_mask:0xc
	v_add_f32_dpp v12, v122, v122 row_ror:8 row_mask:0xf bank_mask:0xc
	v_add_f32_dpp v124, v123, v123 row_ror:8 row_mask:0xf bank_mask:0xc
	s_nop 0
	v_add_f32_dpp v125, v10, v10 row_shl:4 row_mask:0xf bank_mask:0x5
	v_add_f32_dpp v246, v11, v11 row_shl:4 row_mask:0xf bank_mask:0x5
	v_add_f32_dpp v125, v12, v12 row_shr:4 row_mask:0xf bank_mask:0xa
	v_add_f32_dpp v246, v124, v124 row_shr:4 row_mask:0xf bank_mask:0xa
	s_nop 1
	v_add_f32_dpp v247, v125, v125 quad_perm:[2,3,0,1] row_mask:0xf bank_mask:0xf
	v_add_f32_dpp v249, v246, v246 quad_perm:[2,3,0,1] row_mask:0xf bank_mask:0xf
	s_nop 0
	v_cndmask_b32_e64 v252, v249, v247, s[2:3]
	s_nop 1
	v_add_f32_dpp v253, v252, v252 quad_perm:[1,0,3,2] row_mask:0xf bank_mask:0xf
	s_and_saveexec_b64 s[20:21], s[4:5]
	ds_add_f32 v251, v253 offset:2080
	s_mov_b64 exec, s[20:21]
	s_add_i32 s26, s26, 1
	s_add_i32 s20, s26, 1
	s_lshr_b32 s27, s20, 3
	s_and_b32 s27, s27, 3
	s_lshl_b32 s27, s27, 22
	v_add_u32_e32 v230, s27, v250
	s_and_b32 s27, s26, 7
	s_lshl_b32 s27, s27, 6
	v_add_u32_e32 v251, s27, v231
	s_branch .Lgu_iter

; __device__ void phase_gather(const P& p, int vb, int nvb, char* smem) {
;     ...
; #pragma unroll 8
;     for (int bb = 0; bb < 128; bb++) {
;       const uint32_t key = mykl[bb];
;       const int e = (int)(key >> 7);
;       const float wgt = mywl[bb];
;       const uint4* vp = (const uint4*)(V + (size_t)e * 1024 + 16 * j);
;       uint4 vv[4];
; #pragma unroll
;       for (int i = 0; i < 4; i++) vv[i] = vp[i * 16];
;       const f32x2 w2 = f32x2{wgt, wgt};
; #pragma unroll
;       for (int i = 0; i < 4; i++) {
;         const uint32_t w[4] = {vv[i].x, vv[i].y, vv[i].z, vv[i].w};
; #pragma unroll
;         for (int q = 0; q < 4; q++) {
;           acc[i * 8 + q * 2 + 0] += w2 * __builtin_amdgcn_cvt_pk_f32_fp8((int)w[q], false);
;           acc[i * 8 + q * 2 + 1] += w2 * __builtin_amdgcn_cvt_pk_f32_fp8((int)w[q], true);
;         }
;       }
;     }
.Lgv_body:
	s_cmp_eq_u32 s20, 31
	s_cbranch_scc1 .Lgv_last
	s_waitcnt lgkmcnt(0)
	v_and_or_b32 v8, v0, s66, v230
	s_waitcnt vmcnt(15)
	v_cvt_pk_f32_fp8_e32 v[104:105], v150
	v_cvt_pk_f32_fp8_sdwa v[106:107], v150 src0_sel:WORD_1
	v_pk_fma_f32 v[214:215], v[96:97], v[104:105], v[214:215] op_sel_hi:[0,1,1]
	v_pk_fma_f32 v[216:217], v[96:97], v[106:107], v[216:217] op_sel_hi:[0,1,1]
	v_cvt_pk_f32_fp8_e32 v[108:109], v151
	v_cvt_pk_f32_fp8_sdwa v[110:111], v151 src0_sel:WORD_1
	v_pk_fma_f32 v[218:219], v[96:97], v[108:109], v[218:219] op_sel_hi:[0,1,1]
	v_pk_fma_f32 v[220:221], v[96:97], v[110:111], v[220:221] op_sel_hi:[0,1,1]
	v_cvt_pk_f32_fp8_e32 v[104:105], v152
	v_cvt_pk_f32_fp8_sdwa v[106:107], v152 src0_sel:WORD_1
	v_pk_fma_f32 v[222:223], v[96:97], v[104:105], v[222:223] op_sel_hi:[0,1,1]
	v_pk_fma_f32 v[224:225], v[96:97], v[106:107], v[224:225] op_sel_hi:[0,1,1]
	v_cvt_pk_f32_fp8_e32 v[108:109], v153
	v_cvt_pk_f32_fp8_sdwa v[110:111], v153 src0_sel:WORD_1
	v_pk_fma_f32 v[226:227], v[96:97], v[108:109], v[226:227] op_sel_hi:[0,1,1]
	v_pk_fma_f32 v[228:229], v[96:97], v[110:111], v[228:229] op_sel_hi:[0,1,1]
	global_load_dwordx4 v[150:153], v8, s[100:101]
	v_and_or_b32 v9, v1, s66, v230
	s_waitcnt vmcnt(15)
	v_cvt_pk_f32_fp8_e32 v[104:105], v154
	v_cvt_pk_f32_fp8_sdwa v[106:107], v154 src0_sel:WORD_1
	v_pk_fma_f32 v[214:215], v[96:97], v[104:105], v[214:215] op_sel:[1,0,0]
	v_pk_fma_f32 v[216:217], v[96:97], v[106:107], v[216:217] op_sel:[1,0,0]
	v_cvt_pk_f32_fp8_e32 v[108:109], v155
	v_cvt_pk_f32_fp8_sdwa v[110:111], v155 src0_sel:WORD_1
	v_pk_fma_f32 v[218:219], v[96:97], v[108:109], v[218:219] op_sel:[1,0,0]
	v_pk_fma_f32 v[220:221], v[96:97], v[110:111], v[220:221] op_sel:[1,0,0]
	v_cvt_pk_f32_fp8_e32 v[104:105], v156
	v_cvt_pk_f32_fp8_sdwa v[106:107], v156 src0_sel:WORD_1
	v_pk_fma_f32 v[222:223], v[96:97], v[104:105], v[222:223] op_sel:[1,0,0]
	v_pk_fma_f32 v[224:225], v[96:97], v[106:107], v[224:225] op_sel:[1,0,0]
	v_cvt_pk_f32_fp8_e32 v[108:109], v157
	v_cvt_pk_f32_fp8_sdwa v[110:111], v157 src0_sel:WORD_1
	v_pk_fma_f32 v[226:227], v[96:97], v[108:109], v[226:227] op_sel:[1,0,0]
	v_pk_fma_f32 v[228:229], v[96:97], v[110:111], v[228:229] op_sel:[1,0,0]
	global_load_dwordx4 v[154:157], v9, s[100:101]
	ds_read_b128 v[4:7], v254 offset:16
	ds_read_b128 v[100:103], v255 offset:2064
	v_and_or_b32 v8, v2, s66, v230
	s_waitcnt vmcnt(15)
	v_cvt_pk_f32_fp8_e32 v[104:105], v158
	v_cvt_pk_f32_fp8_sdwa v[106:107], v158 src0_sel:WORD_1
	v_pk_fma_f32 v[214:215], v[98:99], v[104:105], v[214:215] op_sel_hi:[0,1,1]
	v_pk_fma_f32 v[216:217], v[98:99], v[106:107], v[216:217] op_sel_hi:[0,1,1]
	v_cvt_pk_f32_fp8_e32 v[108:109], v159
	v_cvt_pk_f32_fp8_sdwa v[110:111], v159 src0_sel:WORD_1
	v_pk_fma_f32 v[218:219], v[98:99], v[108:109], v[218:219] op_sel_hi:[0,1,1]
	v_pk_fma_f32 v[220:221], v[98:99], v[110:111], v[220:221] op_sel_hi:[0,1,1]
	v_cvt_pk_f32_fp8_e32 v[104:105], v160
	v_cvt_pk_f32_fp8_sdwa v[106:107], v160 src0_sel:WORD_1
	v_pk_fma_f32 v[222:223], v[98:99], v[104:105], v[222:223] op_sel_hi:[0,1,1]
	v_pk_fma_f32 v[224:225], v[98:99], v[106:107], v[224:225] op_sel_hi:[0,1,1]
	v_cvt_pk_f32_fp8_e32 v[108:109], v161
	v_cvt_pk_f32_fp8_sdwa v[110:111], v161 src0_sel:WORD_1
	v_pk_fma_f32 v[226:227], v[98:99], v[108:109], v[226:227] op_sel_hi:[0,1,1]
	v_pk_fma_f32 v[228:229], v[98:99], v[110:111], v[228:229] op_sel_hi:[0,1,1]
	global_load_dwordx4 v[158:161], v8, s[100:101]
	v_and_or_b32 v9, v3, s66, v230
	s_waitcnt vmcnt(15)
	v_cvt_pk_f32_fp8_e32 v[104:105], v162
	v_cvt_pk_f32_fp8_sdwa v[106:107], v162 src0_sel:WORD_1
	v_pk_fma_f32 v[214:215], v[98:99], v[104:105], v[214:215] op_sel:[1,0,0]
	v_pk_fma_f32 v[216:217], v[98:99], v[106:107], v[216:217] op_sel:[1,0,0]
	v_cvt_pk_f32_fp8_e32 v[108:109], v163
	v_cvt_pk_f32_fp8_sdwa v[110:111], v163 src0_sel:WORD_1
	v_pk_fma_f32 v[218:219], v[98:99], v[108:109], v[218:219] op_sel:[1,0,0]
	v_pk_fma_f32 v[220:221], v[98:99], v[110:111], v[220:221] op_sel:[1,0,0]
	v_cvt_pk_f32_fp8_e32 v[104:105], v164
	v_cvt_pk_f32_fp8_sdwa v[106:107], v164 src0_sel:WORD_1
	v_pk_fma_f32 v[222:223], v[98:99], v[104:105], v[222:223] op_sel:[1,0,0]
	v_pk_fma_f32 v[224:225], v[98:99], v[106:107], v[224:225] op_sel:[1,0,0]
	v_cvt_pk_f32_fp8_e32 v[108:109], v165
	v_cvt_pk_f32_fp8_sdwa v[110:111], v165 src0_sel:WORD_1
	v_pk_fma_f32 v[226:227], v[98:99], v[108:109], v[226:227] op_sel:[1,0,0]
	v_pk_fma_f32 v[228:229], v[98:99], v[110:111], v[228:229] op_sel:[1,0,0]
	global_load_dwordx4 v[162:165], v9, s[100:101]
	s_waitcnt lgkmcnt(0)
	v_and_or_b32 v8, v4, s66, v230
	s_waitcnt vmcnt(15)
	v_cvt_pk_f32_fp8_e32 v[104:105], v166
	v_cvt_pk_f32_fp8_sdwa v[106:107], v166 src0_sel:WORD_1
	v_pk_fma_f32 v[214:215], v[100:101], v[104:105], v[214:215] op_sel_hi:[0,1,1]
	v_pk_fma_f32 v[216:217], v[100:101], v[106:107], v[216:217] op_sel_hi:[0,1,1]
	v_cvt_pk_f32_fp8_e32 v[108:109], v167
	v_cvt_pk_f32_fp8_sdwa v[110:111], v167 src0_sel:WORD_1
	v_pk_fma_f32 v[218:219], v[100:101], v[108:109], v[218:219] op_sel_hi:[0,1,1]
	v_pk_fma_f32 v[220:221], v[100:101], v[110:111], v[220:221] op_sel_hi:[0,1,1]
	v_cvt_pk_f32_fp8_e32 v[104:105], v168
	v_cvt_pk_f32_fp8_sdwa v[106:107], v168 src0_sel:WORD_1
	v_pk_fma_f32 v[222:223], v[100:101], v[104:105], v[222:223] op_sel_hi:[0,1,1]
	v_pk_fma_f32 v[224:225], v[100:101], v[106:107], v[224:225] op_sel_hi:[0,1,1]
	v_cvt_pk_f32_fp8_e32 v[108:109], v169
	v_cvt_pk_f32_fp8_sdwa v[110:111], v169 src0_sel:WORD_1
	v_pk_fma_f32 v[226:227], v[100:101], v[108:109], v[226:227] op_sel_hi:[0,1,1]
	v_pk_fma_f32 v[228:229], v[100:101], v[110:111], v[228:229] op_sel_hi:[0,1,1]
	global_load_dwordx4 v[166:169], v8, s[100:101]
	v_and_or_b32 v9, v5, s66, v230
	s_waitcnt vmcnt(15)
; __device__ void phase_gather(const P& p, int vb, int nvb, char* smem) {
;     ...
; #pragma unroll 8
;     for (int bb = 0; bb < 128; bb++) {
;       const uint32_t key = mykl[bb];
;       const int e = (int)(key >> 7);
;       const float wgt = mywl[bb];
;       const uint4* vp = (const uint4*)(V + (size_t)e * 1024 + 16 * j);
;       uint4 vv[4];
; #pragma unroll
;       for (int i = 0; i < 4; i++) vv[i] = vp[i * 16];
;       const f32x2 w2 = f32x2{wgt, wgt};
; #pragma unroll
;       for (int i = 0; i < 4; i++) {
;         const uint32_t w[4] = {vv[i].x, vv[i].y, vv[i].z, vv[i].w};
; #pragma unroll
;         for (int q = 0; q < 4; q++) {
;           acc[i * 8 + q * 2 + 0] += w2 * __builtin_amdgcn_cvt_pk_f32_fp8((int)w[q], false);
;           acc[i * 8 + q * 2 + 1] += w2 * __builtin_amdgcn_cvt_pk_f32_fp8((int)w[q], true);
;         }
;       }
;     }
	v_cvt_pk_f32_fp8_e32 v[104:105], v170
	v_cvt_pk_f32_fp8_sdwa v[106:107], v170 src0_sel:WORD_1
	v_pk_fma_f32 v[214:215], v[100:101], v[104:105], v[214:215] op_sel:[1,0,0]
	v_pk_fma_f32 v[216:217], v[100:101], v[106:107], v[216:217] op_sel:[1,0,0]
	v_cvt_pk_f32_fp8_e32 v[108:109], v171
	v_cvt_pk_f32_fp8_sdwa v[110:111], v171 src0_sel:WORD_1
	v_pk_fma_f32 v[218:219], v[100:101], v[108:109], v[218:219] op_sel:[1,0,0]
	v_pk_fma_f32 v[220:221], v[100:101], v[110:111], v[220:221] op_sel:[1,0,0]
	v_cvt_pk_f32_fp8_e32 v[104:105], v172
	v_cvt_pk_f32_fp8_sdwa v[106:107], v172 src0_sel:WORD_1
	v_pk_fma_f32 v[222:223], v[100:101], v[104:105], v[222:223] op_sel:[1,0,0]
	v_pk_fma_f32 v[224:225], v[100:101], v[106:107], v[224:225] op_sel:[1,0,0]
	v_cvt_pk_f32_fp8_e32 v[108:109], v173
	v_cvt_pk_f32_fp8_sdwa v[110:111], v173 src0_sel:WORD_1
	v_pk_fma_f32 v[226:227], v[100:101], v[108:109], v[226:227] op_sel:[1,0,0]
	v_pk_fma_f32 v[228:229], v[100:101], v[110:111], v[228:229] op_sel:[1,0,0]
	global_load_dwordx4 v[170:173], v9, s[100:101]
	ds_read_b128 v[0:3], v254 offset:32
	ds_read_b128 v[96:99], v255 offset:2080
	v_and_or_b32 v8, v6, s66, v230
	s_waitcnt vmcnt(15)
	v_cvt_pk_f32_fp8_e32 v[104:105], v174
	v_cvt_pk_f32_fp8_sdwa v[106:107], v174 src0_sel:WORD_1
	v_pk_fma_f32 v[214:215], v[102:103], v[104:105], v[214:215] op_sel_hi:[0,1,1]
	v_pk_fma_f32 v[216:217], v[102:103], v[106:107], v[216:217] op_sel_hi:[0,1,1]
	v_cvt_pk_f32_fp8_e32 v[108:109], v175
	v_cvt_pk_f32_fp8_sdwa v[110:111], v175 src0_sel:WORD_1
	v_pk_fma_f32 v[218:219], v[102:103], v[108:109], v[218:219] op_sel_hi:[0,1,1]
	v_pk_fma_f32 v[220:221], v[102:103], v[110:111], v[220:221] op_sel_hi:[0,1,1]
	v_cvt_pk_f32_fp8_e32 v[104:105], v176
	v_cvt_pk_f32_fp8_sdwa v[106:107], v176 src0_sel:WORD_1
	v_pk_fma_f32 v[222:223], v[102:103], v[104:105], v[222:223] op_sel_hi:[0,1,1]
	v_pk_fma_f32 v[224:225], v[102:103], v[106:107], v[224:225] op_sel_hi:[0,1,1]
	v_cvt_pk_f32_fp8_e32 v[108:109], v177
	v_cvt_pk_f32_fp8_sdwa v[110:111], v177 src0_sel:WORD_1
	v_pk_fma_f32 v[226:227], v[102:103], v[108:109], v[226:227] op_sel_hi:[0,1,1]
	v_pk_fma_f32 v[228:229], v[102:103], v[110:111], v[228:229] op_sel_hi:[0,1,1]
	global_load_dwordx4 v[174:177], v8, s[100:101]
	v_and_or_b32 v9, v7, s66, v230
	s_waitcnt vmcnt(15)
	v_cvt_pk_f32_fp8_e32 v[104:105], v178
	v_cvt_pk_f32_fp8_sdwa v[106:107], v178 src0_sel:WORD_1
	v_pk_fma_f32 v[214:215], v[102:103], v[104:105], v[214:215] op_sel:[1,0,0]
	v_pk_fma_f32 v[216:217], v[102:103], v[106:107], v[216:217] op_sel:[1,0,0]
	v_cvt_pk_f32_fp8_e32 v[108:109], v179
	v_cvt_pk_f32_fp8_sdwa v[110:111], v179 src0_sel:WORD_1
	v_pk_fma_f32 v[218:219], v[102:103], v[108:109], v[218:219] op_sel:[1,0,0]
	v_pk_fma_f32 v[220:221], v[102:103], v[110:111], v[220:221] op_sel:[1,0,0]
	v_cvt_pk_f32_fp8_e32 v[104:105], v180
	v_cvt_pk_f32_fp8_sdwa v[106:107], v180 src0_sel:WORD_1
	v_pk_fma_f32 v[222:223], v[102:103], v[104:105], v[222:223] op_sel:[1,0,0]
	v_pk_fma_f32 v[224:225], v[102:103], v[106:107], v[224:225] op_sel:[1,0,0]
	v_cvt_pk_f32_fp8_e32 v[108:109], v181
	v_cvt_pk_f32_fp8_sdwa v[110:111], v181 src0_sel:WORD_1
	v_pk_fma_f32 v[226:227], v[102:103], v[108:109], v[226:227] op_sel:[1,0,0]
	v_pk_fma_f32 v[228:229], v[102:103], v[110:111], v[228:229] op_sel:[1,0,0]
	global_load_dwordx4 v[178:181], v9, s[100:101]
	s_waitcnt lgkmcnt(0)
	v_and_or_b32 v8, v0, s66, v230
	s_waitcnt vmcnt(15)
	v_cvt_pk_f32_fp8_e32 v[104:105], v182
	v_cvt_pk_f32_fp8_sdwa v[106:107], v182 src0_sel:WORD_1
	v_pk_fma_f32 v[214:215], v[96:97], v[104:105], v[214:215] op_sel_hi:[0,1,1]
	v_pk_fma_f32 v[216:217], v[96:97], v[106:107], v[216:217] op_sel_hi:[0,1,1]
	v_cvt_pk_f32_fp8_e32 v[108:109], v183
	v_cvt_pk_f32_fp8_sdwa v[110:111], v183 src0_sel:WORD_1
	v_pk_fma_f32 v[218:219], v[96:97], v[108:109], v[218:219] op_sel_hi:[0,1,1]
	v_pk_fma_f32 v[220:221], v[96:97], v[110:111], v[220:221] op_sel_hi:[0,1,1]
	v_cvt_pk_f32_fp8_e32 v[104:105], v184
	v_cvt_pk_f32_fp8_sdwa v[106:107], v184 src0_sel:WORD_1
	v_pk_fma_f32 v[222:223], v[96:97], v[104:105], v[222:223] op_sel_hi:[0,1,1]
	v_pk_fma_f32 v[224:225], v[96:97], v[106:107], v[224:225] op_sel_hi:[0,1,1]
	v_cvt_pk_f32_fp8_e32 v[108:109], v185
	v_cvt_pk_f32_fp8_sdwa v[110:111], v185 src0_sel:WORD_1
	v_pk_fma_f32 v[226:227], v[96:97], v[108:109], v[226:227] op_sel_hi:[0,1,1]
	v_pk_fma_f32 v[228:229], v[96:97], v[110:111], v[228:229] op_sel_hi:[0,1,1]
	global_load_dwordx4 v[182:185], v8, s[100:101]
	v_and_or_b32 v9, v1, s66, v230
	s_waitcnt vmcnt(15)
	v_cvt_pk_f32_fp8_e32 v[104:105], v186
	v_cvt_pk_f32_fp8_sdwa v[106:107], v186 src0_sel:WORD_1
	v_pk_fma_f32 v[214:215], v[96:97], v[104:105], v[214:215] op_sel:[1,0,0]
	v_pk_fma_f32 v[216:217], v[96:97], v[106:107], v[216:217] op_sel:[1,0,0]
	v_cvt_pk_f32_fp8_e32 v[108:109], v187
	v_cvt_pk_f32_fp8_sdwa v[110:111], v187 src0_sel:WORD_1
	v_pk_fma_f32 v[218:219], v[96:97], v[108:109], v[218:219] op_sel:[1,0,0]
	v_pk_fma_f32 v[220:221], v[96:97], v[110:111], v[220:221] op_sel:[1,0,0]
	v_cvt_pk_f32_fp8_e32 v[104:105], v188
	v_cvt_pk_f32_fp8_sdwa v[106:107], v188 src0_sel:WORD_1
	v_pk_fma_f32 v[222:223], v[96:97], v[104:105], v[222:223] op_sel:[1,0,0]
	v_pk_fma_f32 v[224:225], v[96:97], v[106:107], v[224:225] op_sel:[1,0,0]
	v_cvt_pk_f32_fp8_e32 v[108:109], v189
	v_cvt_pk_f32_fp8_sdwa v[110:111], v189 src0_sel:WORD_1
	v_pk_fma_f32 v[226:227], v[96:97], v[108:109], v[226:227] op_sel:[1,0,0]
	v_pk_fma_f32 v[228:229], v[96:97], v[110:111], v[228:229] op_sel:[1,0,0]
	global_load_dwordx4 v[186:189], v9, s[100:101]
	ds_read_b128 v[4:7], v254 offset:48
	ds_read_b128 v[100:103], v255 offset:2096
	v_and_or_b32 v8, v2, s66, v230
	s_waitcnt vmcnt(15)
; __device__ void phase_gather(const P& p, int vb, int nvb, char* smem) {
;     ...
; #pragma unroll 8
;     for (int bb = 0; bb < 128; bb++) {
;       const uint32_t key = mykl[bb];
;       const int e = (int)(key >> 7);
;       const float wgt = mywl[bb];
;       const uint4* vp = (const uint4*)(V + (size_t)e * 1024 + 16 * j);
;       uint4 vv[4];
; #pragma unroll
;       for (int i = 0; i < 4; i++) vv[i] = vp[i * 16];
;       const f32x2 w2 = f32x2{wgt, wgt};
; #pragma unroll
;       for (int i = 0; i < 4; i++) {
;         const uint32_t w[4] = {vv[i].x, vv[i].y, vv[i].z, vv[i].w};
; #pragma unroll
;         for (int q = 0; q < 4; q++) {
;           acc[i * 8 + q * 2 + 0] += w2 * __builtin_amdgcn_cvt_pk_f32_fp8((int)w[q], false);
;           acc[i * 8 + q * 2 + 1] += w2 * __builtin_amdgcn_cvt_pk_f32_fp8((int)w[q], true);
;         }
;       }
;     }
	v_cvt_pk_f32_fp8_e32 v[104:105], v190
	v_cvt_pk_f32_fp8_sdwa v[106:107], v190 src0_sel:WORD_1
	v_pk_fma_f32 v[214:215], v[98:99], v[104:105], v[214:215] op_sel_hi:[0,1,1]
	v_pk_fma_f32 v[216:217], v[98:99], v[106:107], v[216:217] op_sel_hi:[0,1,1]
	v_cvt_pk_f32_fp8_e32 v[108:109], v191
	v_cvt_pk_f32_fp8_sdwa v[110:111], v191 src0_sel:WORD_1
	v_pk_fma_f32 v[218:219], v[98:99], v[108:109], v[218:219] op_sel_hi:[0,1,1]
	v_pk_fma_f32 v[220:221], v[98:99], v[110:111], v[220:221] op_sel_hi:[0,1,1]
	v_cvt_pk_f32_fp8_e32 v[104:105], v192
	v_cvt_pk_f32_fp8_sdwa v[106:107], v192 src0_sel:WORD_1
	v_pk_fma_f32 v[222:223], v[98:99], v[104:105], v[222:223] op_sel_hi:[0,1,1]
	v_pk_fma_f32 v[224:225], v[98:99], v[106:107], v[224:225] op_sel_hi:[0,1,1]
	v_cvt_pk_f32_fp8_e32 v[108:109], v193
	v_cvt_pk_f32_fp8_sdwa v[110:111], v193 src0_sel:WORD_1
	v_pk_fma_f32 v[226:227], v[98:99], v[108:109], v[226:227] op_sel_hi:[0,1,1]
	v_pk_fma_f32 v[228:229], v[98:99], v[110:111], v[228:229] op_sel_hi:[0,1,1]
	global_load_dwordx4 v[190:193], v8, s[100:101]
	v_and_or_b32 v9, v3, s66, v230
	s_waitcnt vmcnt(15)
	v_cvt_pk_f32_fp8_e32 v[104:105], v194
	v_cvt_pk_f32_fp8_sdwa v[106:107], v194 src0_sel:WORD_1
	v_pk_fma_f32 v[214:215], v[98:99], v[104:105], v[214:215] op_sel:[1,0,0]
	v_pk_fma_f32 v[216:217], v[98:99], v[106:107], v[216:217] op_sel:[1,0,0]
	v_cvt_pk_f32_fp8_e32 v[108:109], v195
	v_cvt_pk_f32_fp8_sdwa v[110:111], v195 src0_sel:WORD_1
	v_pk_fma_f32 v[218:219], v[98:99], v[108:109], v[218:219] op_sel:[1,0,0]
	v_pk_fma_f32 v[220:221], v[98:99], v[110:111], v[220:221] op_sel:[1,0,0]
	v_cvt_pk_f32_fp8_e32 v[104:105], v196
	v_cvt_pk_f32_fp8_sdwa v[106:107], v196 src0_sel:WORD_1
	v_pk_fma_f32 v[222:223], v[98:99], v[104:105], v[222:223] op_sel:[1,0,0]
	v_pk_fma_f32 v[224:225], v[98:99], v[106:107], v[224:225] op_sel:[1,0,0]
	v_cvt_pk_f32_fp8_e32 v[108:109], v197
	v_cvt_pk_f32_fp8_sdwa v[110:111], v197 src0_sel:WORD_1
	v_pk_fma_f32 v[226:227], v[98:99], v[108:109], v[226:227] op_sel:[1,0,0]
	v_pk_fma_f32 v[228:229], v[98:99], v[110:111], v[228:229] op_sel:[1,0,0]
	global_load_dwordx4 v[194:197], v9, s[100:101]
	s_waitcnt lgkmcnt(0)
	v_and_or_b32 v8, v4, s66, v230
	s_waitcnt vmcnt(15)
	v_cvt_pk_f32_fp8_e32 v[104:105], v198
	v_cvt_pk_f32_fp8_sdwa v[106:107], v198 src0_sel:WORD_1
	v_pk_fma_f32 v[214:215], v[100:101], v[104:105], v[214:215] op_sel_hi:[0,1,1]
	v_pk_fma_f32 v[216:217], v[100:101], v[106:107], v[216:217] op_sel_hi:[0,1,1]
	v_cvt_pk_f32_fp8_e32 v[108:109], v199
	v_cvt_pk_f32_fp8_sdwa v[110:111], v199 src0_sel:WORD_1
	v_pk_fma_f32 v[218:219], v[100:101], v[108:109], v[218:219] op_sel_hi:[0,1,1]
	v_pk_fma_f32 v[220:221], v[100:101], v[110:111], v[220:221] op_sel_hi:[0,1,1]
	v_cvt_pk_f32_fp8_e32 v[104:105], v200
	v_cvt_pk_f32_fp8_sdwa v[106:107], v200 src0_sel:WORD_1
	v_pk_fma_f32 v[222:223], v[100:101], v[104:105], v[222:223] op_sel_hi:[0,1,1]
	v_pk_fma_f32 v[224:225], v[100:101], v[106:107], v[224:225] op_sel_hi:[0,1,1]
	v_cvt_pk_f32_fp8_e32 v[108:109], v201
	v_cvt_pk_f32_fp8_sdwa v[110:111], v201 src0_sel:WORD_1
	v_pk_fma_f32 v[226:227], v[100:101], v[108:109], v[226:227] op_sel_hi:[0,1,1]
	v_pk_fma_f32 v[228:229], v[100:101], v[110:111], v[228:229] op_sel_hi:[0,1,1]
	global_load_dwordx4 v[198:201], v8, s[100:101]
	s_add_i32 s27, s20, 2
	s_and_b32 s27, s27, 7
	s_lshl_b32 s27, s27, 6
	v_add_u32_e32 v254, s27, v133
	s_add_i32 s27, s20, 1
	s_and_b32 s27, s27, 7
	s_lshl_b32 s27, s27, 6
	v_add_u32_e32 v255, s27, v133
	v_and_or_b32 v9, v5, s66, v230
	s_waitcnt vmcnt(15)
	v_cvt_pk_f32_fp8_e32 v[104:105], v202
	v_cvt_pk_f32_fp8_sdwa v[106:107], v202 src0_sel:WORD_1
	v_pk_fma_f32 v[214:215], v[100:101], v[104:105], v[214:215] op_sel:[1,0,0]
	v_pk_fma_f32 v[216:217], v[100:101], v[106:107], v[216:217] op_sel:[1,0,0]
	v_cvt_pk_f32_fp8_e32 v[108:109], v203
	v_cvt_pk_f32_fp8_sdwa v[110:111], v203 src0_sel:WORD_1
	v_pk_fma_f32 v[218:219], v[100:101], v[108:109], v[218:219] op_sel:[1,0,0]
	v_pk_fma_f32 v[220:221], v[100:101], v[110:111], v[220:221] op_sel:[1,0,0]
	v_cvt_pk_f32_fp8_e32 v[104:105], v204
	v_cvt_pk_f32_fp8_sdwa v[106:107], v204 src0_sel:WORD_1
	v_pk_fma_f32 v[222:223], v[100:101], v[104:105], v[222:223] op_sel:[1,0,0]
	v_pk_fma_f32 v[224:225], v[100:101], v[106:107], v[224:225] op_sel:[1,0,0]
	v_cvt_pk_f32_fp8_e32 v[108:109], v205
	v_cvt_pk_f32_fp8_sdwa v[110:111], v205 src0_sel:WORD_1
	v_pk_fma_f32 v[226:227], v[100:101], v[108:109], v[226:227] op_sel:[1,0,0]
	v_pk_fma_f32 v[228:229], v[100:101], v[110:111], v[228:229] op_sel:[1,0,0]
	global_load_dwordx4 v[202:205], v9, s[100:101]
	ds_read_b128 v[0:3], v254
	ds_read_b128 v[96:99], v255 offset:2048
	v_and_or_b32 v8, v6, s66, v230
	s_waitcnt vmcnt(15)
	v_cvt_pk_f32_fp8_e32 v[104:105], v206
	v_cvt_pk_f32_fp8_sdwa v[106:107], v206 src0_sel:WORD_1
	v_pk_fma_f32 v[214:215], v[102:103], v[104:105], v[214:215] op_sel_hi:[0,1,1]
	v_pk_fma_f32 v[216:217], v[102:103], v[106:107], v[216:217] op_sel_hi:[0,1,1]
	v_cvt_pk_f32_fp8_e32 v[108:109], v207
	v_cvt_pk_f32_fp8_sdwa v[110:111], v207 src0_sel:WORD_1
	v_pk_fma_f32 v[218:219], v[102:103], v[108:109], v[218:219] op_sel_hi:[0,1,1]
	v_pk_fma_f32 v[220:221], v[102:103], v[110:111], v[220:221] op_sel_hi:[0,1,1]
	v_cvt_pk_f32_fp8_e32 v[104:105], v208
	v_cvt_pk_f32_fp8_sdwa v[106:107], v208 src0_sel:WORD_1
	v_pk_fma_f32 v[222:223], v[102:103], v[104:105], v[222:223] op_sel_hi:[0,1,1]
	v_pk_fma_f32 v[224:225], v[102:103], v[106:107], v[224:225] op_sel_hi:[0,1,1]
	v_cvt_pk_f32_fp8_e32 v[108:109], v209
	v_cvt_pk_f32_fp8_sdwa v[110:111], v209 src0_sel:WORD_1
	v_pk_fma_f32 v[226:227], v[102:103], v[108:109], v[226:227] op_sel_hi:[0,1,1]
	v_pk_fma_f32 v[228:229], v[102:103], v[110:111], v[228:229] op_sel_hi:[0,1,1]
	global_load_dwordx4 v[206:209], v8, s[100:101]
	v_and_or_b32 v9, v7, s66, v230
	s_waitcnt vmcnt(15)
	v_cvt_pk_f32_fp8_e32 v[104:105], v210
	v_cvt_pk_f32_fp8_sdwa v[106:107], v210 src0_sel:WORD_1
	v_pk_fma_f32 v[214:215], v[102:103], v[104:105], v[214:215] op_sel:[1,0,0]
	v_pk_fma_f32 v[216:217], v[102:103], v[106:107], v[216:217] op_sel:[1,0,0]
	v_cvt_pk_f32_fp8_e32 v[108:109], v211
	v_cvt_pk_f32_fp8_sdwa v[110:111], v211 src0_sel:WORD_1
	v_pk_fma_f32 v[218:219], v[102:103], v[108:109], v[218:219] op_sel:[1,0,0]
	v_pk_fma_f32 v[220:221], v[102:103], v[110:111], v[220:221] op_sel:[1,0,0]
	v_cvt_pk_f32_fp8_e32 v[104:105], v212
	v_cvt_pk_f32_fp8_sdwa v[106:107], v212 src0_sel:WORD_1
	v_pk_fma_f32 v[222:223], v[102:103], v[104:105], v[222:223] op_sel:[1,0,0]
	v_pk_fma_f32 v[224:225], v[102:103], v[106:107], v[224:225] op_sel:[1,0,0]
	v_cvt_pk_f32_fp8_e32 v[108:109], v213
	v_cvt_pk_f32_fp8_sdwa v[110:111], v213 src0_sel:WORD_1
	v_pk_fma_f32 v[226:227], v[102:103], v[108:109], v[226:227] op_sel:[1,0,0]
	v_pk_fma_f32 v[228:229], v[102:103], v[110:111], v[228:229] op_sel:[1,0,0]
	global_load_dwordx4 v[210:213], v9, s[100:101]
	s_add_i32 s20, s20, 1
	s_add_i32 s26, s20, 1
	s_lshr_b32 s27, s26, 3
	s_and_b32 s27, s27, 3
	s_lshl_b32 s27, s27, 22
	v_add_u32_e32 v230, s27, v250
	s_and_b32 s27, s20, 7
	s_cmp_lg_u32 s27, 0
	s_cbranch_scc1 .Lgv_body
; __device__ void phase_gather(const P& p, int vb, int nvb, char* smem) {
;     ...
;     f32x2 acc[32];
; #pragma unroll
;     for (int i = 0; i < 32; i++) acc[i] = f32x2{0.f, 0.f};
; #pragma unroll 8
;     for (int bb = 0; bb < 128; bb++) {
;       const uint32_t key = mykl[bb];
;       const int e = (int)(key >> 7);
;       const float wgt = mywl[bb];
;       const uint4* vp = (const uint4*)(V + (size_t)e * 1024 + 16 * j);
;       uint4 vv[4];
; #pragma unroll
;       for (int i = 0; i < 4; i++) vv[i] = vp[i * 16];
;       const f32x2 w2 = f32x2{wgt, wgt};
; #pragma unroll
;       for (int i = 0; i < 4; i++) {
;         const uint32_t w[4] = {vv[i].x, vv[i].y, vv[i].z, vv[i].w};
; #pragma unroll
;         for (int q = 0; q < 4; q++) {
;           acc[i * 8 + q * 2 + 0] += w2 * __builtin_amdgcn_cvt_pk_f32_fp8((int)w[q], false);
;           acc[i * 8 + q * 2 + 1] += w2 * __builtin_amdgcn_cvt_pk_f32_fp8((int)w[q], true);
;         }
;       }
;     }
	s_sub_u32 s26, s20, 1
	s_lshr_b32 s27, s26, 3
	s_and_b32 s27, s27, 3
	s_cmp_eq_u32 s27, 0
	s_cbranch_scc1 .Lgv_s_0
	s_cmp_eq_u32 s27, 1
	s_cbranch_scc1 .Lgv_s_1
	s_cmp_eq_u32 s27, 2
	s_cbranch_scc1 .Lgv_s_2
	v_mov_b32_e32 v46, v214
	v_mov_b32_e32 v47, v215
	v_mov_b32_e32 v44, v216
	v_mov_b32_e32 v45, v217
	v_mov_b32_e32 v42, v218
	v_mov_b32_e32 v43, v219
	v_mov_b32_e32 v40, v220
	v_mov_b32_e32 v41, v221
	v_mov_b32_e32 v38, v222
	v_mov_b32_e32 v39, v223
	v_mov_b32_e32 v36, v224
	v_mov_b32_e32 v37, v225
	v_mov_b32_e32 v34, v226
	v_mov_b32_e32 v35, v227
	v_mov_b32_e32 v32, v228
	v_mov_b32_e32 v33, v229
	s_branch .Lgv_s_x
